# RMSNorm row loops: loop-invariant gamma loads hoisted out of the loop, store-serialising vmcnt waits removed
# speedup vs baseline: 1.0197x; 1.0051x over previous
.LBB0_42:
	s_or_b64 exec, exec, s[16:17]
	s_cmpk_gt_i32 s6, 0x3fff
	v_mbcnt_lo_u32_b32 v153, -1, 0
	s_cbranch_scc1 .LBB0_45
	s_load_dwordx2 s[8:9], s[8:9], 0x10
	v_lshlrev_b32_e32 v8, 4, v7
	v_mbcnt_hi_u32_b32 v7, -1, v153
	v_mov_b32_e32 v9, 0
	v_and_b32_e32 v10, 64, v7
	s_waitcnt lgkmcnt(0)
	global_load_dwordx4 v[0:3], v8, s[8:9]
	v_lshl_add_u64 v[20:21], s[4:5], 0, v[8:9]
	v_lshl_add_u64 v[22:23], s[8:9], 0, v[8:9]
	v_xor_b32_e32 v8, 16, v7
	v_add_u32_e32 v10, 64, v10
	v_cmp_lt_i32_e32 vcc, v8, v10
	s_mov_b64 s[4:5], 0x2d00000
	s_mov_b32 s8, 0x3a800000
	v_cndmask_b32_e32 v8, v7, v8, vcc
	v_lshlrev_b32_e32 v27, 2, v8
	v_xor_b32_e32 v8, 32, v7
	v_cmp_lt_i32_e32 vcc, v8, v10
	v_mov_b32_e32 v26, 0x358637bd
	s_mov_b32 s9, 0x800000
	v_cndmask_b32_e32 v7, v7, v8, vcc
	v_lshlrev_b32_e32 v28, 2, v7
	v_mov_b32_e32 v7, v9
	v_lshl_add_u64 v[4:5], v[4:5], 0, v[6:7]
	v_lshl_add_u64 v[24:25], v[4:5], 0, s[4:5]
	global_load_dwordx4 v[200:203], v[22:23], off offset:1024
	global_load_dwordx4 v[204:207], v[22:23], off offset:2048
	global_load_dwordx4 v[208:211], v[22:23], off offset:3072
.LBB0_44:
	s_ashr_i32 s7, s6, 31
	s_lshl_b64 s[4:5], s[6:7], 12
	s_add_i32 s10, s6, s28
	v_lshl_add_u64 v[8:9], v[20:21], 0, s[4:5]
	s_ashr_i32 s11, s10, 31
	global_load_dwordx4 v[30:33], v[8:9], off
	global_load_dwordx4 v[34:37], v[8:9], off offset:1024
	global_load_dwordx4 v[4:7], v[8:9], off offset:3072
	global_load_dwordx4 v[16:19], v[8:9], off offset:2048
	s_lshl_b64 s[4:5], s[10:11], 12
	v_lshl_add_u64 v[46:47], v[20:21], 0, s[4:5]
	global_load_dwordx4 v[38:41], v[46:47], off
	global_load_dwordx4 v[42:45], v[46:47], off offset:1024
	global_load_dwordx4 v[8:11], v[46:47], off offset:3072
	global_load_dwordx4 v[12:15], v[46:47], off offset:2048
	s_lshl_b64 s[6:7], s[6:7], 11
	s_waitcnt vmcnt(7)
	v_pk_mul_f32 v[46:47], v[32:33], v[32:33]
	v_pk_mul_f32 v[48:49], v[30:31], v[30:31]
	s_waitcnt vmcnt(6)
	v_pk_mul_f32 v[50:51], v[36:37], v[36:37]
	v_pk_mul_f32 v[52:53], v[34:35], v[34:35]
	s_waitcnt vmcnt(4)
	v_mul_f32_e32 v54, v17, v17
	v_mul_f32_e32 v56, v19, v19
	v_pk_mov_b32 v[58:59], v[48:49], v[46:47] op_sel:[1,0]
	v_mov_b32_e32 v49, v47
	s_waitcnt vmcnt(3)
	v_pk_mul_f32 v[46:47], v[40:41], v[40:41]
	v_pk_mul_f32 v[60:61], v[38:39], v[38:39]
	v_pk_mov_b32 v[62:63], v[52:53], v[50:51] op_sel:[1,0]
	v_mov_b32_e32 v53, v51
	s_waitcnt vmcnt(2)
	v_pk_mul_f32 v[50:51], v[44:45], v[44:45]
	v_pk_mul_f32 v[64:65], v[42:43], v[42:43]
	v_mul_f32_e32 v69, v6, v6
	v_mul_f32_e32 v70, v7, v7
	v_pk_fma_f32 v[54:55], v[16:17], v[16:17], v[54:55] op_sel_hi:[1,1,0]
	v_pk_fma_f32 v[56:57], v[18:19], v[18:19], v[56:57] op_sel_hi:[1,1,0]
	v_pk_add_f32 v[48:49], v[58:59], v[48:49]
	v_pk_mov_b32 v[58:59], v[60:61], v[46:47] op_sel:[1,0]
	v_mov_b32_e32 v61, v47
	v_pk_add_f32 v[46:47], v[62:63], v[52:53]
	v_pk_mov_b32 v[52:53], v[64:65], v[50:51] op_sel:[1,0]
	v_mov_b32_e32 v65, v51
	v_mul_f32_e32 v67, v5, v5
	s_waitcnt vmcnt(0)
	v_mul_f32_e32 v66, v13, v13
	v_mul_f32_e32 v68, v15, v15
	v_mov_b32_e32 v55, v69
	v_mov_b32_e32 v57, v70
	v_pk_add_f32 v[58:59], v[58:59], v[60:61]
	v_pk_add_f32 v[52:53], v[52:53], v[64:65]
	v_mul_f32_e32 v29, v4, v4
	v_mul_f32_e32 v71, v8, v8
	v_mul_f32_e32 v72, v9, v9
	v_mul_f32_e32 v73, v10, v10
	v_mul_f32_e32 v74, v11, v11
	v_pk_fma_f32 v[50:51], v[12:13], v[12:13], v[66:67] op_sel_hi:[1,1,0]
	v_pk_fma_f32 v[62:63], v[14:15], v[14:15], v[68:69] op_sel_hi:[1,1,0]
	v_pk_add_f32 v[48:49], v[48:49], v[48:49] op_sel:[0,1] op_sel_hi:[1,0]
	v_pk_add_f32 v[46:47], v[46:47], v[46:47] op_sel:[0,1] op_sel_hi:[1,0]
	v_pk_add_f32 v[54:55], v[54:55], v[56:57]
	v_pk_add_f32 v[56:57], v[58:59], v[58:59] op_sel:[0,1] op_sel_hi:[1,0]
	v_pk_add_f32 v[52:53], v[52:53], v[52:53] op_sel:[0,1] op_sel_hi:[1,0]
	v_mov_b32_e32 v51, v73
	v_mov_b32_e32 v63, v74
	v_mov_b32_e32 v49, v29
	v_mov_b32_e32 v47, v67
	v_mov_b32_e32 v57, v71
	v_mov_b32_e32 v53, v72
	v_pk_add_f32 v[50:51], v[50:51], v[62:63]
	v_pk_add_f32 v[46:47], v[48:49], v[46:47]
	v_pk_add_f32 v[48:49], v[56:57], v[52:53]
	v_pk_add_f32 v[46:47], v[46:47], v[54:55]
	v_pk_add_f32 v[48:49], v[48:49], v[50:51]
	v_mov_b32_e32 v51, v46
	v_mov_b32_e32 v50, v48
	v_mov_b32_e32 v46, v49
	v_pk_add_f32 v[46:47], v[50:51], v[46:47]
	s_nop 1
	v_mov_b32_dpp v49, v47 quad_perm:[1,0,3,2] row_mask:0xf bank_mask:0xf bound_ctrl:1
	v_mov_b32_dpp v48, v46 quad_perm:[1,0,3,2] row_mask:0xf bank_mask:0xf bound_ctrl:1
	v_pk_add_f32 v[46:47], v[46:47], v[48:49]
	s_nop 1
	v_mov_b32_dpp v49, v47 quad_perm:[2,3,0,1] row_mask:0xf bank_mask:0xf bound_ctrl:1
	v_mov_b32_dpp v48, v46 quad_perm:[2,3,0,1] row_mask:0xf bank_mask:0xf bound_ctrl:1
	v_pk_add_f32 v[46:47], v[46:47], v[48:49]
	s_nop 1
	v_mov_b32_dpp v49, v47 row_half_mirror row_mask:0xf bank_mask:0xf bound_ctrl:1
	v_mov_b32_dpp v48, v46 row_half_mirror row_mask:0xf bank_mask:0xf bound_ctrl:1
	v_pk_add_f32 v[46:47], v[46:47], v[48:49]
	s_nop 1
	v_mov_b32_dpp v49, v47 row_mirror row_mask:0xf bank_mask:0xf bound_ctrl:1
	v_mov_b32_dpp v48, v46 row_mirror row_mask:0xf bank_mask:0xf bound_ctrl:1
	v_pk_add_f32 v[46:47], v[46:47], v[48:49]
	ds_bpermute_b32 v49, v27, v47
	ds_bpermute_b32 v48, v27, v46
	s_waitcnt lgkmcnt(0)
	v_pk_add_f32 v[46:47], v[46:47], v[48:49]
	ds_bpermute_b32 v49, v28, v47
	ds_bpermute_b32 v48, v28, v46
	s_waitcnt lgkmcnt(0)
	v_pk_add_f32 v[46:47], v[46:47], v[48:49]
	s_nop 0
	v_pk_fma_f32 v[46:47], v[46:47], s[8:9], v[26:27] op_sel_hi:[1,0,0]
	s_nop 0
	v_mul_f32_e32 v29, 0x4b800000, v47
	v_cmp_gt_f32_e32 vcc, s9, v47
	v_mul_f32_e32 v48, 0x4b800000, v46
	v_cmp_gt_f32_e64 s[4:5], s9, v46
	v_cndmask_b32_e32 v29, v47, v29, vcc
	v_rsq_f32_e32 v29, v29
	v_cndmask_b32_e64 v46, v46, v48, s[4:5]
	v_rsq_f32_e32 v48, v46
	v_lshl_add_u64 v[46:47], v[24:25], 0, s[6:7]
	v_mul_f32_e32 v49, 0x45800000, v29
	v_cndmask_b32_e32 v29, v29, v49, vcc
	v_mul_f32_e32 v50, 0x45800000, v48
	v_cndmask_b32_e64 v48, v48, v50, s[4:5]
	v_mul_f32_e32 v30, v30, v29
	v_mul_f32_e32 v31, v31, v29
	v_mul_f32_e32 v32, v32, v29
	v_mul_f32_e32 v33, v33, v29
	v_mul_f32_e32 v38, v38, v48
	v_mul_f32_e32 v39, v39, v48
	v_mul_f32_e32 v30, v0, v30
	v_mul_f32_e32 v31, v1, v31
	v_mul_f32_e32 v40, v40, v48
	v_mul_f32_e32 v41, v41, v48
	v_mul_f32_e32 v32, v2, v32
	v_mul_f32_e32 v33, v3, v33
	v_mul_f32_e32 v38, v0, v38
	v_mul_f32_e32 v39, v1, v39
	v_cvt_pk_bf16_f32 v30, v30, v31
	v_cvt_pk_bf16_f32 v31, v32, v33
	v_mul_f32_e32 v40, v2, v40
	v_mul_f32_e32 v41, v3, v41
	global_store_dwordx2 v[46:47], v[30:31], off
	v_cvt_pk_bf16_f32 v38, v38, v39
	v_cvt_pk_bf16_f32 v39, v40, v41
	s_lshl_b64 s[4:5], s[10:11], 11
	v_lshl_add_u64 v[40:41], v[24:25], 0, s[4:5]
	v_mul_f32_e32 v34, v34, v29
	v_mul_f32_e32 v35, v35, v29
	v_mul_f32_e32 v36, v36, v29
	v_mul_f32_e32 v37, v37, v29
	v_mul_f32_e32 v42, v42, v48
	v_mul_f32_e32 v43, v43, v48
	v_mul_f32_e32 v44, v44, v48
	v_mul_f32_e32 v45, v45, v48
	global_store_dwordx2 v[40:41], v[38:39], off
	v_mul_f32_e32 v16, v16, v29
	v_mul_f32_e32 v17, v17, v29
	v_mul_f32_e32 v18, v18, v29
	v_mul_f32_e32 v19, v19, v29
	v_mul_f32_e32 v12, v12, v48
	v_mul_f32_e32 v13, v13, v48
	v_mul_f32_e32 v14, v14, v48
	v_mul_f32_e32 v15, v15, v48
	v_mul_f32_e32 v4, v4, v29
	v_mul_f32_e32 v5, v5, v29
	s_add_i32 s6, s10, s28
	v_mul_f32_e32 v6, v6, v29
	v_mul_f32_e32 v7, v7, v29
	v_mul_f32_e32 v8, v8, v48
	v_mul_f32_e32 v9, v9, v48
	v_mul_f32_e32 v10, v10, v48
	v_mul_f32_e32 v11, v11, v48
	s_cmpk_lt_i32 s6, 0x4000
	v_mul_f32_e32 v34, v34, v200
	v_mul_f32_e32 v35, v35, v201
	v_mul_f32_e32 v36, v36, v202
	v_mul_f32_e32 v37, v37, v203
	v_mul_f32_e32 v38, v200, v42
	v_mul_f32_e32 v39, v201, v43
	v_mul_f32_e32 v32, v202, v44
	v_mul_f32_e32 v33, v203, v45
	v_cvt_pk_bf16_f32 v30, v34, v35
	v_cvt_pk_bf16_f32 v31, v36, v37
	global_store_dwordx2 v[46:47], v[30:31], off offset:512
	v_cvt_pk_bf16_f32 v34, v38, v39
	v_cvt_pk_bf16_f32 v35, v32, v33
	v_mul_f32_e32 v16, v16, v204
	global_store_dwordx2 v[40:41], v[34:35], off offset:512
	v_mul_f32_e32 v17, v17, v205
	v_mul_f32_e32 v18, v18, v206
	v_mul_f32_e32 v19, v19, v207
	v_mul_f32_e32 v30, v12, v204
	v_mul_f32_e32 v31, v13, v205
	v_mul_f32_e32 v14, v14, v206
	v_mul_f32_e32 v15, v15, v207
	v_cvt_pk_bf16_f32 v12, v16, v17
	v_cvt_pk_bf16_f32 v13, v18, v19
	global_store_dwordx2 v[46:47], v[12:13], off offset:1024
	v_cvt_pk_bf16_f32 v16, v30, v31
	v_cvt_pk_bf16_f32 v17, v14, v15
	v_mul_f32_e32 v4, v4, v208
	v_mul_f32_e32 v5, v5, v209
	global_store_dwordx2 v[40:41], v[16:17], off offset:1024
	v_mul_f32_e32 v6, v6, v210
	v_mul_f32_e32 v7, v7, v211
	v_cvt_pk_bf16_f32 v4, v4, v5
	v_cvt_pk_bf16_f32 v5, v6, v7
	v_mul_f32_e32 v8, v8, v208
	v_mul_f32_e32 v9, v9, v209
	v_mul_f32_e32 v10, v10, v210
	v_mul_f32_e32 v11, v11, v211
	global_store_dwordx2 v[46:47], v[4:5], off offset:1536
	v_cvt_pk_bf16_f32 v4, v8, v9
	v_cvt_pk_bf16_f32 v5, v10, v11
	global_store_dwordx2 v[40:41], v[4:5], off offset:1536
	s_cbranch_scc1 .LBB0_44

.LBB0_727:
	s_or_b64 exec, exec, s[42:43]
	s_waitcnt lgkmcnt(0)
	s_barrier
	s_mov_b32 s4, 0
	s_load_dwordx2 s[6:7], s[0:1], 0xe0
	s_ashr_i32 s5, s4, 31
	v_mov_b32_e32 v30, v152
	s_mov_b32 s20, s38
	s_waitcnt lgkmcnt(0)
	s_add_u32 s10, s6, s4
	v_readfirstlane_b32 s6, v30
	s_addc_u32 s11, s7, s5
	s_ashr_i32 s21, s6, 6
	s_mov_b32 s6, s2
	s_lshl_b32 s6, s6, 3
	s_add_i32 s18, s6, s21
	s_lshl_b32 s19, s20, 3
	s_lshl_b64 s[6:7], s[4:5], 3
	s_add_u32 s8, s0, s6
	v_and_b32_e32 v29, 63, v30
	s_addc_u32 s9, s1, s7
	s_cmpk_gt_i32 s18, 0x3fff
	v_lshlrev_b32_e32 v20, 3, v29
	s_cbranch_scc1 .LBB0_730
	s_load_dwordx2 s[6:7], s[8:9], 0xb8
	s_load_dwordx2 s[14:15], s[0:1], 0xd8
	v_lshlrev_b32_e32 v4, 4, v29
	s_lshl_b64 s[4:5], s[4:5], 2
	v_mov_b32_e32 v5, 0
	s_waitcnt lgkmcnt(0)
	global_load_dwordx4 v[0:3], v4, s[6:7]
	s_add_u32 s4, s14, s4
	s_addc_u32 s5, s15, s5
	v_and_b32_e32 v6, 64, v153
	v_lshl_add_u64 v[22:23], s[4:5], 0, v[4:5]
	v_lshl_add_u64 v[24:25], s[6:7], 0, v[4:5]
	v_xor_b32_e32 v4, 16, v153
	v_add_u32_e32 v6, 64, v6
	v_cmp_lt_i32_e32 vcc, v4, v6
	v_mov_b32_e32 v21, v5
	s_mov_b64 s[4:5], 0x2d00000
	v_cndmask_b32_e32 v4, v153, v4, vcc
	v_lshlrev_b32_e32 v31, 2, v4
	v_xor_b32_e32 v4, 32, v153
	v_cmp_lt_i32_e32 vcc, v4, v6
	s_mov_b32 s6, 0x3a800000
	v_mov_b32_e32 v28, 0x358637bd
	v_cndmask_b32_e32 v4, v153, v4, vcc
	v_lshlrev_b32_e32 v32, 2, v4
	v_lshl_add_u64 v[4:5], s[10:11], 0, v[20:21]
	v_lshl_add_u64 v[26:27], v[4:5], 0, s[4:5]
	s_mov_b32 s7, 0x800000
	s_mov_b32 s16, s18
	global_load_dwordx4 v[200:203], v[24:25], off offset:1024
	global_load_dwordx4 v[204:207], v[24:25], off offset:2048
	global_load_dwordx4 v[208:211], v[24:25], off offset:3072
.LBB0_729:
	s_ashr_i32 s17, s16, 31
	s_lshl_b64 s[4:5], s[16:17], 12
	s_add_i32 s14, s16, s19
	s_waitcnt vmcnt(8)
	v_lshl_add_u64 v[8:9], v[22:23], 0, s[4:5]
	s_ashr_i32 s15, s14, 31
	global_load_dwordx4 v[34:37], v[8:9], off
	global_load_dwordx4 v[38:41], v[8:9], off offset:1024
	global_load_dwordx4 v[4:7], v[8:9], off offset:3072
	global_load_dwordx4 v[16:19], v[8:9], off offset:2048
	s_lshl_b64 s[4:5], s[14:15], 12
	v_lshl_add_u64 v[50:51], v[22:23], 0, s[4:5]
	global_load_dwordx4 v[42:45], v[50:51], off
	global_load_dwordx4 v[46:49], v[50:51], off offset:1024
	global_load_dwordx4 v[8:11], v[50:51], off offset:3072
	global_load_dwordx4 v[12:15], v[50:51], off offset:2048
	s_lshl_b64 s[16:17], s[16:17], 11
	s_waitcnt vmcnt(7)
	v_pk_mul_f32 v[50:51], v[36:37], v[36:37]
	v_pk_mul_f32 v[52:53], v[34:35], v[34:35]
	s_waitcnt vmcnt(6)
	v_pk_mul_f32 v[54:55], v[40:41], v[40:41]
	v_pk_mul_f32 v[56:57], v[38:39], v[38:39]
	s_waitcnt vmcnt(4)
	v_mul_f32_e32 v58, v17, v17
	v_mul_f32_e32 v60, v19, v19
	v_pk_mov_b32 v[62:63], v[52:53], v[50:51] op_sel:[1,0]
	v_mov_b32_e32 v53, v51
	s_waitcnt vmcnt(3)
	v_pk_mul_f32 v[50:51], v[44:45], v[44:45]
	v_pk_mul_f32 v[64:65], v[42:43], v[42:43]
	v_pk_mov_b32 v[66:67], v[56:57], v[54:55] op_sel:[1,0]
	v_mov_b32_e32 v57, v55
	s_waitcnt vmcnt(2)
	v_pk_mul_f32 v[54:55], v[48:49], v[48:49]
	v_pk_mul_f32 v[68:69], v[46:47], v[46:47]
	v_mul_f32_e32 v71, v6, v6
	v_mul_f32_e32 v73, v7, v7
	v_pk_fma_f32 v[58:59], v[16:17], v[16:17], v[58:59] op_sel_hi:[1,1,0]
	v_pk_fma_f32 v[60:61], v[18:19], v[18:19], v[60:61] op_sel_hi:[1,1,0]
	v_pk_add_f32 v[52:53], v[62:63], v[52:53]
	v_pk_mov_b32 v[62:63], v[64:65], v[50:51] op_sel:[1,0]
	v_mov_b32_e32 v65, v51
	v_pk_add_f32 v[50:51], v[66:67], v[56:57]
	v_pk_mov_b32 v[56:57], v[68:69], v[54:55] op_sel:[1,0]
	v_mov_b32_e32 v69, v55
	s_waitcnt vmcnt(0)
	v_mul_f32_e32 v70, v13, v13
	v_mul_f32_e32 v72, v15, v15
	v_mov_b32_e32 v59, v71
	v_mov_b32_e32 v61, v73
	v_pk_add_f32 v[62:63], v[62:63], v[64:65]
	v_pk_add_f32 v[56:57], v[56:57], v[68:69]
	v_mul_f32_e32 v21, v4, v4
	v_mul_f32_e32 v33, v5, v5
	v_mul_f32_e32 v74, v8, v8
	v_mul_f32_e32 v75, v9, v9
	v_mul_f32_e32 v76, v10, v10
	v_mul_f32_e32 v77, v11, v11
	v_pk_fma_f32 v[54:55], v[12:13], v[12:13], v[70:71] op_sel_hi:[1,1,0]
	v_pk_fma_f32 v[66:67], v[14:15], v[14:15], v[72:73] op_sel_hi:[1,1,0]
	v_pk_add_f32 v[52:53], v[52:53], v[52:53] op_sel:[0,1] op_sel_hi:[1,0]
	v_pk_add_f32 v[50:51], v[50:51], v[50:51] op_sel:[0,1] op_sel_hi:[1,0]
	v_pk_add_f32 v[58:59], v[58:59], v[60:61]
	v_pk_add_f32 v[60:61], v[62:63], v[62:63] op_sel:[0,1] op_sel_hi:[1,0]
	v_pk_add_f32 v[56:57], v[56:57], v[56:57] op_sel:[0,1] op_sel_hi:[1,0]
	v_mov_b32_e32 v55, v76
	v_mov_b32_e32 v67, v77
	v_mov_b32_e32 v53, v21
	v_mov_b32_e32 v51, v33
	v_mov_b32_e32 v61, v74
	v_mov_b32_e32 v57, v75
	v_pk_add_f32 v[54:55], v[54:55], v[66:67]
	v_pk_add_f32 v[50:51], v[52:53], v[50:51]
	v_pk_add_f32 v[52:53], v[60:61], v[56:57]
	v_pk_add_f32 v[50:51], v[50:51], v[58:59]
	v_pk_add_f32 v[52:53], v[52:53], v[54:55]
	v_mov_b32_e32 v55, v50
	v_mov_b32_e32 v54, v52
	v_mov_b32_e32 v50, v53
	v_pk_add_f32 v[50:51], v[54:55], v[50:51]
	s_nop 1
	v_mov_b32_dpp v53, v51 quad_perm:[1,0,3,2] row_mask:0xf bank_mask:0xf bound_ctrl:1
	v_mov_b32_dpp v52, v50 quad_perm:[1,0,3,2] row_mask:0xf bank_mask:0xf bound_ctrl:1
	v_pk_add_f32 v[50:51], v[50:51], v[52:53]
	s_nop 1
	v_mov_b32_dpp v53, v51 quad_perm:[2,3,0,1] row_mask:0xf bank_mask:0xf bound_ctrl:1
	v_mov_b32_dpp v52, v50 quad_perm:[2,3,0,1] row_mask:0xf bank_mask:0xf bound_ctrl:1
	v_pk_add_f32 v[50:51], v[50:51], v[52:53]
	s_nop 1
	v_mov_b32_dpp v53, v51 row_half_mirror row_mask:0xf bank_mask:0xf bound_ctrl:1
	v_mov_b32_dpp v52, v50 row_half_mirror row_mask:0xf bank_mask:0xf bound_ctrl:1
	v_pk_add_f32 v[50:51], v[50:51], v[52:53]
	s_nop 1
	v_mov_b32_dpp v53, v51 row_mirror row_mask:0xf bank_mask:0xf bound_ctrl:1
	v_mov_b32_dpp v52, v50 row_mirror row_mask:0xf bank_mask:0xf bound_ctrl:1
	v_pk_add_f32 v[50:51], v[50:51], v[52:53]
	ds_bpermute_b32 v53, v31, v51
	ds_bpermute_b32 v52, v31, v50
	s_waitcnt lgkmcnt(0)
	v_pk_add_f32 v[50:51], v[50:51], v[52:53]
	ds_bpermute_b32 v53, v32, v51
	ds_bpermute_b32 v52, v32, v50
	s_waitcnt lgkmcnt(0)
	v_pk_add_f32 v[50:51], v[50:51], v[52:53]
	s_nop 0
	v_pk_fma_f32 v[50:51], v[50:51], s[6:7], v[28:29] op_sel_hi:[1,0,0]
	s_nop 0
	v_mul_f32_e32 v21, 0x4b800000, v51
	v_cmp_gt_f32_e32 vcc, s7, v51
	v_mul_f32_e32 v33, 0x4b800000, v50
	v_cmp_gt_f32_e64 s[4:5], s7, v50
	v_cndmask_b32_e32 v21, v51, v21, vcc
	v_rsq_f32_e32 v21, v21
	v_cndmask_b32_e64 v33, v50, v33, s[4:5]
	v_rsq_f32_e32 v33, v33
	v_lshl_add_u64 v[50:51], v[26:27], 0, s[16:17]
	v_mul_f32_e32 v52, 0x45800000, v21
	v_cndmask_b32_e32 v21, v21, v52, vcc
	v_mul_f32_e32 v53, 0x45800000, v33
	v_cndmask_b32_e64 v33, v33, v53, s[4:5]
	v_mul_f32_e32 v34, v34, v21
	v_mul_f32_e32 v35, v35, v21
	v_mul_f32_e32 v36, v36, v21
	v_mul_f32_e32 v37, v37, v21
	v_mul_f32_e32 v42, v42, v33
	v_mul_f32_e32 v43, v43, v33
	v_mul_f32_e32 v34, v0, v34
	v_mul_f32_e32 v35, v1, v35
	v_mul_f32_e32 v44, v44, v33
	v_mul_f32_e32 v45, v45, v33
	v_mul_f32_e32 v36, v2, v36
	v_mul_f32_e32 v37, v3, v37
	v_mul_f32_e32 v42, v0, v42
	v_mul_f32_e32 v43, v1, v43
	v_cvt_pk_bf16_f32 v34, v34, v35
	v_cvt_pk_bf16_f32 v35, v36, v37
	v_mul_f32_e32 v44, v2, v44
	v_mul_f32_e32 v45, v3, v45
	global_store_dwordx2 v[50:51], v[34:35], off
	v_cvt_pk_bf16_f32 v42, v42, v43
	v_cvt_pk_bf16_f32 v43, v44, v45
	s_lshl_b64 s[4:5], s[14:15], 11
	v_lshl_add_u64 v[44:45], v[26:27], 0, s[4:5]
	v_mul_f32_e32 v38, v38, v21
	v_mul_f32_e32 v39, v39, v21
	v_mul_f32_e32 v40, v40, v21
	v_mul_f32_e32 v41, v41, v21
	v_mul_f32_e32 v46, v46, v33
	v_mul_f32_e32 v47, v47, v33
	v_mul_f32_e32 v48, v48, v33
	v_mul_f32_e32 v49, v49, v33
	global_store_dwordx2 v[44:45], v[42:43], off
	v_mul_f32_e32 v16, v16, v21
	v_mul_f32_e32 v17, v17, v21
	v_mul_f32_e32 v18, v18, v21
	v_mul_f32_e32 v19, v19, v21
	v_mul_f32_e32 v12, v12, v33
	v_mul_f32_e32 v13, v13, v33
	v_mul_f32_e32 v14, v14, v33
	v_mul_f32_e32 v15, v15, v33
	v_mul_f32_e32 v4, v4, v21
	v_mul_f32_e32 v5, v5, v21
	s_add_i32 s16, s14, s19
	v_mul_f32_e32 v6, v6, v21
	v_mul_f32_e32 v7, v7, v21
	v_mul_f32_e32 v8, v8, v33
	v_mul_f32_e32 v9, v9, v33
	v_mul_f32_e32 v10, v10, v33
	v_mul_f32_e32 v11, v11, v33
	s_cmpk_gt_i32 s16, 0x3fff
	v_mul_f32_e32 v38, v38, v200
	v_mul_f32_e32 v39, v39, v201
	v_mul_f32_e32 v40, v40, v202
	v_mul_f32_e32 v41, v41, v203
	v_mul_f32_e32 v42, v200, v46
	v_mul_f32_e32 v43, v201, v47
	v_mul_f32_e32 v36, v202, v48
	v_mul_f32_e32 v37, v203, v49
	v_cvt_pk_bf16_f32 v34, v38, v39
	v_cvt_pk_bf16_f32 v35, v40, v41
	global_store_dwordx2 v[50:51], v[34:35], off offset:512
	v_cvt_pk_bf16_f32 v38, v42, v43
	v_cvt_pk_bf16_f32 v39, v36, v37
	v_mul_f32_e32 v16, v16, v204
	global_store_dwordx2 v[44:45], v[38:39], off offset:512
	v_mul_f32_e32 v17, v17, v205
	v_mul_f32_e32 v18, v18, v206
	v_mul_f32_e32 v19, v19, v207
	v_mul_f32_e32 v34, v12, v204
	v_mul_f32_e32 v35, v13, v205
	v_mul_f32_e32 v14, v14, v206
	v_mul_f32_e32 v15, v15, v207
	v_cvt_pk_bf16_f32 v12, v16, v17
	v_cvt_pk_bf16_f32 v13, v18, v19
	global_store_dwordx2 v[50:51], v[12:13], off offset:1024
	v_cvt_pk_bf16_f32 v16, v34, v35
	v_cvt_pk_bf16_f32 v17, v14, v15
	v_mul_f32_e32 v4, v4, v208
	v_mul_f32_e32 v5, v5, v209
	global_store_dwordx2 v[44:45], v[16:17], off offset:1024
	v_mul_f32_e32 v6, v6, v210
	v_mul_f32_e32 v7, v7, v211
	v_cvt_pk_bf16_f32 v4, v4, v5
	v_cvt_pk_bf16_f32 v5, v6, v7
	v_mul_f32_e32 v8, v8, v208
	v_mul_f32_e32 v9, v9, v209
	v_mul_f32_e32 v10, v10, v210
	v_mul_f32_e32 v11, v11, v211
	global_store_dwordx2 v[50:51], v[4:5], off offset:1536
	v_cvt_pk_bf16_f32 v4, v8, v9
	v_cvt_pk_bf16_f32 v5, v10, v11
	global_store_dwordx2 v[44:45], v[4:5], off offset:1536
	s_cbranch_scc0 .LBB0_729

.LBB0_924:
	s_or_b64 exec, exec, s[10:11]
	s_ashr_i32 s10, s19, 6
	s_lshl_b32 s11, s20, 3
	s_add_i32 s10, s11, s10
	s_cmpk_gt_i32 s10, 0x3fff
	s_cbranch_scc1 .LBB0_927
	s_lshl_b32 s14, s18, 3
	s_lshl_b64 s[16:17], s[8:9], 2
	s_add_u32 s4, s4, s16
	s_addc_u32 s5, s5, s17
	s_lshl_b64 s[8:9], s[8:9], 3
	s_add_u32 s8, s0, s8
	s_addc_u32 s9, s1, s9
	s_load_dwordx2 s[8:9], s[8:9], 0x10
	v_and_b32_e32 v8, 63, v2
	v_lshlrev_b32_e32 v4, 4, v8
	v_mov_b32_e32 v5, 0
	v_lshl_add_u64 v[20:21], s[4:5], 0, v[4:5]
	s_waitcnt lgkmcnt(0)
	v_lshl_add_u64 v[6:7], s[8:9], 0, v[4:5]
	s_movk_i32 s8, 0x1000
	v_add_co_u32_e32 v0, vcc, s8, v6
	s_mov_b64 s[4:5], 0x1000
	s_nop 0
	v_addc_co_u32_e32 v1, vcc, 0, v7, vcc
	global_load_dwordx4 v[0:3], v[0:1], off
	v_lshl_add_u64 v[22:23], v[6:7], 0, s[4:5]
	v_and_b32_e32 v6, 64, v153
	v_xor_b32_e32 v4, 16, v153
	v_add_u32_e32 v6, 64, v6
	v_cmp_lt_i32_e32 vcc, v4, v6
	s_mov_b64 s[4:5], 0x2d00000
	v_mov_b32_e32 v26, 0x358637bd
	v_cndmask_b32_e32 v4, v153, v4, vcc
	v_lshlrev_b32_e32 v27, 2, v4
	v_xor_b32_e32 v4, 32, v153
	v_cmp_lt_i32_e32 vcc, v4, v6
	s_nop 1
	v_cndmask_b32_e32 v4, v153, v4, vcc
	v_lshlrev_b32_e32 v28, 2, v4
	v_lshlrev_b32_e32 v4, 3, v8
	v_lshl_add_u64 v[4:5], s[6:7], 0, v[4:5]
	v_lshl_add_u64 v[24:25], v[4:5], 0, s[4:5]
	s_mov_b32 s6, 0x3a800000
	s_mov_b32 s7, 0x800000
	global_load_dwordx4 v[200:203], v[22:23], off offset:1024
	global_load_dwordx4 v[204:207], v[22:23], off offset:2048
	global_load_dwordx4 v[208:211], v[22:23], off offset:3072
.LBB0_926:
	s_ashr_i32 s11, s10, 31
	s_lshl_b64 s[4:5], s[10:11], 12
	s_add_i32 s8, s10, s14
	v_lshl_add_u64 v[8:9], v[20:21], 0, s[4:5]
	s_ashr_i32 s9, s8, 31
	global_load_dwordx4 v[30:33], v[8:9], off
	global_load_dwordx4 v[34:37], v[8:9], off offset:1024
	global_load_dwordx4 v[4:7], v[8:9], off offset:3072
	global_load_dwordx4 v[16:19], v[8:9], off offset:2048
	s_lshl_b64 s[4:5], s[8:9], 12
	v_lshl_add_u64 v[46:47], v[20:21], 0, s[4:5]
	global_load_dwordx4 v[38:41], v[46:47], off
	global_load_dwordx4 v[42:45], v[46:47], off offset:1024
	global_load_dwordx4 v[8:11], v[46:47], off offset:3072
	global_load_dwordx4 v[12:15], v[46:47], off offset:2048
	s_lshl_b64 s[10:11], s[10:11], 11
	s_waitcnt vmcnt(7)
	v_pk_mul_f32 v[46:47], v[32:33], v[32:33]
	v_pk_mul_f32 v[48:49], v[30:31], v[30:31]
	s_waitcnt vmcnt(6)
	v_pk_mul_f32 v[50:51], v[36:37], v[36:37]
	v_pk_mul_f32 v[52:53], v[34:35], v[34:35]
	s_waitcnt vmcnt(4)
	v_mul_f32_e32 v54, v17, v17
	v_mul_f32_e32 v56, v19, v19
	v_pk_mov_b32 v[58:59], v[48:49], v[46:47] op_sel:[1,0]
	v_mov_b32_e32 v49, v47
	s_waitcnt vmcnt(3)
	v_pk_mul_f32 v[46:47], v[40:41], v[40:41]
	v_pk_mul_f32 v[60:61], v[38:39], v[38:39]
	v_pk_mov_b32 v[62:63], v[52:53], v[50:51] op_sel:[1,0]
	v_mov_b32_e32 v53, v51
	s_waitcnt vmcnt(2)
	v_pk_mul_f32 v[50:51], v[44:45], v[44:45]
	v_pk_mul_f32 v[64:65], v[42:43], v[42:43]
	v_mul_f32_e32 v69, v6, v6
	v_mul_f32_e32 v70, v7, v7
	v_pk_fma_f32 v[54:55], v[16:17], v[16:17], v[54:55] op_sel_hi:[1,1,0]
	v_pk_fma_f32 v[56:57], v[18:19], v[18:19], v[56:57] op_sel_hi:[1,1,0]
	v_pk_add_f32 v[48:49], v[58:59], v[48:49]
	v_pk_mov_b32 v[58:59], v[60:61], v[46:47] op_sel:[1,0]
	v_mov_b32_e32 v61, v47
	v_pk_add_f32 v[46:47], v[62:63], v[52:53]
	v_pk_mov_b32 v[52:53], v[64:65], v[50:51] op_sel:[1,0]
	v_mov_b32_e32 v65, v51
	v_mul_f32_e32 v67, v5, v5
	s_waitcnt vmcnt(0)
	v_mul_f32_e32 v66, v13, v13
	v_mul_f32_e32 v68, v15, v15
	v_mov_b32_e32 v55, v69
	v_mov_b32_e32 v57, v70
	v_pk_add_f32 v[58:59], v[58:59], v[60:61]
	v_pk_add_f32 v[52:53], v[52:53], v[64:65]
	v_mul_f32_e32 v29, v4, v4
	v_mul_f32_e32 v71, v8, v8
	v_mul_f32_e32 v72, v9, v9
	v_mul_f32_e32 v73, v10, v10
	v_mul_f32_e32 v74, v11, v11
	v_pk_fma_f32 v[50:51], v[12:13], v[12:13], v[66:67] op_sel_hi:[1,1,0]
	v_pk_fma_f32 v[62:63], v[14:15], v[14:15], v[68:69] op_sel_hi:[1,1,0]
	v_pk_add_f32 v[48:49], v[48:49], v[48:49] op_sel:[0,1] op_sel_hi:[1,0]
	v_pk_add_f32 v[46:47], v[46:47], v[46:47] op_sel:[0,1] op_sel_hi:[1,0]
	v_pk_add_f32 v[54:55], v[54:55], v[56:57]
	v_pk_add_f32 v[56:57], v[58:59], v[58:59] op_sel:[0,1] op_sel_hi:[1,0]
	v_pk_add_f32 v[52:53], v[52:53], v[52:53] op_sel:[0,1] op_sel_hi:[1,0]
	v_mov_b32_e32 v51, v73
	v_mov_b32_e32 v63, v74
	v_mov_b32_e32 v49, v29
	v_mov_b32_e32 v47, v67
	v_mov_b32_e32 v57, v71
	v_mov_b32_e32 v53, v72
	v_pk_add_f32 v[50:51], v[50:51], v[62:63]
	v_pk_add_f32 v[46:47], v[48:49], v[46:47]
	v_pk_add_f32 v[48:49], v[56:57], v[52:53]
	v_pk_add_f32 v[46:47], v[46:47], v[54:55]
	v_pk_add_f32 v[48:49], v[48:49], v[50:51]
	v_mov_b32_e32 v51, v46
	v_mov_b32_e32 v50, v48
	v_mov_b32_e32 v46, v49
	v_pk_add_f32 v[46:47], v[50:51], v[46:47]
	s_nop 1
	v_mov_b32_dpp v49, v47 quad_perm:[1,0,3,2] row_mask:0xf bank_mask:0xf bound_ctrl:1
	v_mov_b32_dpp v48, v46 quad_perm:[1,0,3,2] row_mask:0xf bank_mask:0xf bound_ctrl:1
	v_pk_add_f32 v[46:47], v[46:47], v[48:49]
	s_nop 1
	v_mov_b32_dpp v49, v47 quad_perm:[2,3,0,1] row_mask:0xf bank_mask:0xf bound_ctrl:1
	v_mov_b32_dpp v48, v46 quad_perm:[2,3,0,1] row_mask:0xf bank_mask:0xf bound_ctrl:1
	v_pk_add_f32 v[46:47], v[46:47], v[48:49]
	s_nop 1
	v_mov_b32_dpp v49, v47 row_half_mirror row_mask:0xf bank_mask:0xf bound_ctrl:1
	v_mov_b32_dpp v48, v46 row_half_mirror row_mask:0xf bank_mask:0xf bound_ctrl:1
	v_pk_add_f32 v[46:47], v[46:47], v[48:49]
	s_nop 1
	v_mov_b32_dpp v49, v47 row_mirror row_mask:0xf bank_mask:0xf bound_ctrl:1
	v_mov_b32_dpp v48, v46 row_mirror row_mask:0xf bank_mask:0xf bound_ctrl:1
	v_pk_add_f32 v[46:47], v[46:47], v[48:49]
	ds_bpermute_b32 v49, v27, v47
	ds_bpermute_b32 v48, v27, v46
	s_waitcnt lgkmcnt(0)
	v_pk_add_f32 v[46:47], v[46:47], v[48:49]
	ds_bpermute_b32 v49, v28, v47
	ds_bpermute_b32 v48, v28, v46
	s_waitcnt lgkmcnt(0)
	v_pk_add_f32 v[46:47], v[46:47], v[48:49]
	s_nop 0
	v_pk_fma_f32 v[46:47], v[46:47], s[6:7], v[26:27] op_sel_hi:[1,0,0]
	s_nop 0
	v_mul_f32_e32 v29, 0x4b800000, v47
	v_cmp_gt_f32_e32 vcc, s7, v47
	v_mul_f32_e32 v48, 0x4b800000, v46
	v_cmp_gt_f32_e64 s[4:5], s7, v46
	v_cndmask_b32_e32 v29, v47, v29, vcc
	v_rsq_f32_e32 v29, v29
	v_cndmask_b32_e64 v46, v46, v48, s[4:5]
	v_rsq_f32_e32 v48, v46
	v_lshl_add_u64 v[46:47], v[24:25], 0, s[10:11]
	v_mul_f32_e32 v49, 0x45800000, v29
	v_cndmask_b32_e32 v29, v29, v49, vcc
	v_mul_f32_e32 v50, 0x45800000, v48
	v_cndmask_b32_e64 v48, v48, v50, s[4:5]
	v_mul_f32_e32 v30, v30, v29
	v_mul_f32_e32 v31, v31, v29
	v_mul_f32_e32 v32, v32, v29
	v_mul_f32_e32 v33, v33, v29
	v_mul_f32_e32 v38, v38, v48
	v_mul_f32_e32 v39, v39, v48
	v_mul_f32_e32 v30, v0, v30
	v_mul_f32_e32 v31, v1, v31
	v_mul_f32_e32 v40, v40, v48
	v_mul_f32_e32 v41, v41, v48
	v_mul_f32_e32 v32, v2, v32
	v_mul_f32_e32 v33, v3, v33
	v_mul_f32_e32 v38, v0, v38
	v_mul_f32_e32 v39, v1, v39
	v_cvt_pk_bf16_f32 v30, v30, v31
	v_cvt_pk_bf16_f32 v31, v32, v33
	v_mul_f32_e32 v40, v2, v40
	v_mul_f32_e32 v41, v3, v41
	global_store_dwordx2 v[46:47], v[30:31], off
	v_cvt_pk_bf16_f32 v38, v38, v39
	v_cvt_pk_bf16_f32 v39, v40, v41
	s_lshl_b64 s[4:5], s[8:9], 11
	v_lshl_add_u64 v[40:41], v[24:25], 0, s[4:5]
	v_mul_f32_e32 v34, v34, v29
	v_mul_f32_e32 v35, v35, v29
	v_mul_f32_e32 v36, v36, v29
	v_mul_f32_e32 v37, v37, v29
	v_mul_f32_e32 v42, v42, v48
	v_mul_f32_e32 v43, v43, v48
	v_mul_f32_e32 v44, v44, v48
	v_mul_f32_e32 v45, v45, v48
	global_store_dwordx2 v[40:41], v[38:39], off
	v_mul_f32_e32 v16, v16, v29
	v_mul_f32_e32 v17, v17, v29
	v_mul_f32_e32 v18, v18, v29
	v_mul_f32_e32 v19, v19, v29
	v_mul_f32_e32 v12, v12, v48
	v_mul_f32_e32 v13, v13, v48
	v_mul_f32_e32 v14, v14, v48
	v_mul_f32_e32 v15, v15, v48
	v_mul_f32_e32 v4, v4, v29
	v_mul_f32_e32 v5, v5, v29
	s_add_i32 s10, s8, s14
	v_mul_f32_e32 v6, v6, v29
	v_mul_f32_e32 v7, v7, v29
	v_mul_f32_e32 v8, v8, v48
	v_mul_f32_e32 v9, v9, v48
	v_mul_f32_e32 v10, v10, v48
	v_mul_f32_e32 v11, v11, v48
	s_cmpk_lt_i32 s10, 0x4000
	v_mul_f32_e32 v34, v34, v200
	v_mul_f32_e32 v35, v35, v201
	v_mul_f32_e32 v36, v36, v202
	v_mul_f32_e32 v37, v37, v203
	v_mul_f32_e32 v38, v200, v42
	v_mul_f32_e32 v39, v201, v43
	v_mul_f32_e32 v32, v202, v44
	v_mul_f32_e32 v33, v203, v45
	v_cvt_pk_bf16_f32 v30, v34, v35
	v_cvt_pk_bf16_f32 v31, v36, v37
	global_store_dwordx2 v[46:47], v[30:31], off offset:512
	v_cvt_pk_bf16_f32 v34, v38, v39
	v_cvt_pk_bf16_f32 v35, v32, v33
	v_mul_f32_e32 v16, v16, v204
	global_store_dwordx2 v[40:41], v[34:35], off offset:512
	v_mul_f32_e32 v17, v17, v205
	v_mul_f32_e32 v18, v18, v206
	v_mul_f32_e32 v19, v19, v207
	v_mul_f32_e32 v30, v12, v204
	v_mul_f32_e32 v31, v13, v205
	v_mul_f32_e32 v14, v14, v206
	v_mul_f32_e32 v15, v15, v207
	v_cvt_pk_bf16_f32 v12, v16, v17
	v_cvt_pk_bf16_f32 v13, v18, v19
	global_store_dwordx2 v[46:47], v[12:13], off offset:1024
	v_cvt_pk_bf16_f32 v16, v30, v31
	v_cvt_pk_bf16_f32 v17, v14, v15
	v_mul_f32_e32 v4, v4, v208
	v_mul_f32_e32 v5, v5, v209
	global_store_dwordx2 v[40:41], v[16:17], off offset:1024
	v_mul_f32_e32 v6, v6, v210
	v_mul_f32_e32 v7, v7, v211
	v_cvt_pk_bf16_f32 v4, v4, v5
	v_cvt_pk_bf16_f32 v5, v6, v7
	v_mul_f32_e32 v8, v8, v208
	v_mul_f32_e32 v9, v9, v209
	v_mul_f32_e32 v10, v10, v210
	v_mul_f32_e32 v11, v11, v211
	global_store_dwordx2 v[46:47], v[4:5], off offset:1536
	v_cvt_pk_bf16_f32 v4, v8, v9
	v_cvt_pk_bf16_f32 v5, v10, v11
	global_store_dwordx2 v[40:41], v[4:5], off offset:1536
	s_cbranch_scc1 .LBB0_926

.LBB0_1609:
	s_or_b64 exec, exec, s[42:43]
	v_mov_b32_e32 v0, v152
	s_waitcnt lgkmcnt(0)
	s_barrier
	s_mov_b32 s4, 0
	s_mov_b32 s7, s2
	v_readfirstlane_b32 s5, v0
	s_ashr_i32 s6, s5, 6
	s_mov_b32 s5, s38
	s_lshl_b32 s7, s7, 3
	s_add_i32 s10, s7, s6
	s_cmpk_gt_i32 s10, 0x3fff
	s_cbranch_scc1 .LBB0_1612
	s_lshl_b32 s7, s5, 3
	s_ashr_i32 s5, s4, 31
	s_lshl_b64 s[8:9], s[4:5], 3
	s_add_u32 s8, s0, s8
	s_addc_u32 s9, s1, s9
	s_load_dwordx2 s[8:9], s[8:9], 0xb8
	v_and_b32_e32 v8, 63, v0
	v_mov_b32_e32 v5, 0
	v_lshlrev_b32_e32 v4, 4, v8
	s_movk_i32 s6, 0x1000
	s_load_dwordx4 s[16:19], s[0:1], 0xd8
	s_waitcnt lgkmcnt(0)
	v_lshl_add_u64 v[6:7], s[8:9], 0, v[4:5]
	v_add_co_u32_e32 v0, vcc, s6, v6
	s_mov_b32 s6, 0x3a800000
	s_nop 0
	v_addc_co_u32_e32 v1, vcc, 0, v7, vcc
	global_load_dwordx4 v[0:3], v[0:1], off
	s_add_u32 s8, s18, s4
	s_addc_u32 s9, s19, s5
	s_lshl_b64 s[4:5], s[4:5], 2
	s_add_u32 s4, s16, s4
	s_addc_u32 s5, s17, s5
	v_lshl_add_u64 v[20:21], s[4:5], 0, v[4:5]
	s_mov_b64 s[4:5], 0x1000
	v_lshl_add_u64 v[22:23], v[6:7], 0, s[4:5]
	v_and_b32_e32 v6, 64, v153
	v_xor_b32_e32 v4, 16, v153
	v_add_u32_e32 v6, 64, v6
	v_cmp_lt_i32_e32 vcc, v4, v6
	s_mov_b64 s[4:5], 0x2d00000
	v_mov_b32_e32 v26, 0x358637bd
	v_cndmask_b32_e32 v4, v153, v4, vcc
	v_lshlrev_b32_e32 v27, 2, v4
	v_xor_b32_e32 v4, 32, v153
	v_cmp_lt_i32_e32 vcc, v4, v6
	s_mov_b32 s14, 0x800000
	s_nop 0
	v_cndmask_b32_e32 v4, v153, v4, vcc
	v_lshlrev_b32_e32 v28, 2, v4
	v_lshlrev_b32_e32 v4, 3, v8
	v_lshl_add_u64 v[4:5], s[8:9], 0, v[4:5]
	v_lshl_add_u64 v[24:25], v[4:5], 0, s[4:5]
	global_load_dwordx4 v[200:203], v[22:23], off offset:1024
	global_load_dwordx4 v[204:207], v[22:23], off offset:2048
	global_load_dwordx4 v[208:211], v[22:23], off offset:3072
.LBB0_1611:
	s_ashr_i32 s11, s10, 31
	s_lshl_b64 s[4:5], s[10:11], 12
	s_add_i32 s8, s10, s7
	s_waitcnt vmcnt(8)
	v_lshl_add_u64 v[8:9], v[20:21], 0, s[4:5]
	s_ashr_i32 s9, s8, 31
	global_load_dwordx4 v[30:33], v[8:9], off
	global_load_dwordx4 v[34:37], v[8:9], off offset:1024
	global_load_dwordx4 v[4:7], v[8:9], off offset:3072
	global_load_dwordx4 v[16:19], v[8:9], off offset:2048
	s_lshl_b64 s[4:5], s[8:9], 12
	v_lshl_add_u64 v[46:47], v[20:21], 0, s[4:5]
	global_load_dwordx4 v[38:41], v[46:47], off
	global_load_dwordx4 v[42:45], v[46:47], off offset:1024
	global_load_dwordx4 v[8:11], v[46:47], off offset:3072
	global_load_dwordx4 v[12:15], v[46:47], off offset:2048
	s_lshl_b64 s[10:11], s[10:11], 11
	s_waitcnt vmcnt(7)
	v_pk_mul_f32 v[46:47], v[32:33], v[32:33]
	v_pk_mul_f32 v[48:49], v[30:31], v[30:31]
	s_waitcnt vmcnt(6)
	v_pk_mul_f32 v[50:51], v[36:37], v[36:37]
	v_pk_mul_f32 v[52:53], v[34:35], v[34:35]
	s_waitcnt vmcnt(4)
	v_mul_f32_e32 v54, v17, v17
	v_mul_f32_e32 v56, v19, v19
	v_pk_mov_b32 v[58:59], v[48:49], v[46:47] op_sel:[1,0]
	v_mov_b32_e32 v49, v47
	s_waitcnt vmcnt(3)
	v_pk_mul_f32 v[46:47], v[40:41], v[40:41]
	v_pk_mul_f32 v[60:61], v[38:39], v[38:39]
	v_pk_mov_b32 v[62:63], v[52:53], v[50:51] op_sel:[1,0]
	v_mov_b32_e32 v53, v51
	s_waitcnt vmcnt(2)
	v_pk_mul_f32 v[50:51], v[44:45], v[44:45]
	v_pk_mul_f32 v[64:65], v[42:43], v[42:43]
	v_mul_f32_e32 v69, v6, v6
	v_mul_f32_e32 v70, v7, v7
	v_pk_fma_f32 v[54:55], v[16:17], v[16:17], v[54:55] op_sel_hi:[1,1,0]
	v_pk_fma_f32 v[56:57], v[18:19], v[18:19], v[56:57] op_sel_hi:[1,1,0]
	v_pk_add_f32 v[48:49], v[58:59], v[48:49]
	v_pk_mov_b32 v[58:59], v[60:61], v[46:47] op_sel:[1,0]
	v_mov_b32_e32 v61, v47
	v_pk_add_f32 v[46:47], v[62:63], v[52:53]
	v_pk_mov_b32 v[52:53], v[64:65], v[50:51] op_sel:[1,0]
	v_mov_b32_e32 v65, v51
	v_mul_f32_e32 v67, v5, v5
	s_waitcnt vmcnt(0)
	v_mul_f32_e32 v66, v13, v13
	v_mul_f32_e32 v68, v15, v15
	v_mov_b32_e32 v55, v69
	v_mov_b32_e32 v57, v70
	v_pk_add_f32 v[58:59], v[58:59], v[60:61]
	v_pk_add_f32 v[52:53], v[52:53], v[64:65]
	v_mul_f32_e32 v29, v4, v4
	v_mul_f32_e32 v71, v8, v8
	v_mul_f32_e32 v72, v9, v9
	v_mul_f32_e32 v73, v10, v10
	v_mul_f32_e32 v74, v11, v11
	v_pk_fma_f32 v[50:51], v[12:13], v[12:13], v[66:67] op_sel_hi:[1,1,0]
	v_pk_fma_f32 v[62:63], v[14:15], v[14:15], v[68:69] op_sel_hi:[1,1,0]
	v_pk_add_f32 v[48:49], v[48:49], v[48:49] op_sel:[0,1] op_sel_hi:[1,0]
	v_pk_add_f32 v[46:47], v[46:47], v[46:47] op_sel:[0,1] op_sel_hi:[1,0]
	v_pk_add_f32 v[54:55], v[54:55], v[56:57]
	v_pk_add_f32 v[56:57], v[58:59], v[58:59] op_sel:[0,1] op_sel_hi:[1,0]
	v_pk_add_f32 v[52:53], v[52:53], v[52:53] op_sel:[0,1] op_sel_hi:[1,0]
	v_mov_b32_e32 v51, v73
	v_mov_b32_e32 v63, v74
	v_mov_b32_e32 v49, v29
	v_mov_b32_e32 v47, v67
	v_mov_b32_e32 v57, v71
	v_mov_b32_e32 v53, v72
	v_pk_add_f32 v[50:51], v[50:51], v[62:63]
	v_pk_add_f32 v[46:47], v[48:49], v[46:47]
	v_pk_add_f32 v[48:49], v[56:57], v[52:53]
	v_pk_add_f32 v[46:47], v[46:47], v[54:55]
	v_pk_add_f32 v[48:49], v[48:49], v[50:51]
	v_mov_b32_e32 v51, v46
	v_mov_b32_e32 v50, v48
	v_mov_b32_e32 v46, v49
	v_pk_add_f32 v[46:47], v[50:51], v[46:47]
	s_nop 1
	v_mov_b32_dpp v49, v47 quad_perm:[1,0,3,2] row_mask:0xf bank_mask:0xf bound_ctrl:1
	v_mov_b32_dpp v48, v46 quad_perm:[1,0,3,2] row_mask:0xf bank_mask:0xf bound_ctrl:1
	v_pk_add_f32 v[46:47], v[46:47], v[48:49]
	s_nop 1
	v_mov_b32_dpp v49, v47 quad_perm:[2,3,0,1] row_mask:0xf bank_mask:0xf bound_ctrl:1
	v_mov_b32_dpp v48, v46 quad_perm:[2,3,0,1] row_mask:0xf bank_mask:0xf bound_ctrl:1
	v_pk_add_f32 v[46:47], v[46:47], v[48:49]
	s_nop 1
	v_mov_b32_dpp v49, v47 row_half_mirror row_mask:0xf bank_mask:0xf bound_ctrl:1
	v_mov_b32_dpp v48, v46 row_half_mirror row_mask:0xf bank_mask:0xf bound_ctrl:1
	v_pk_add_f32 v[46:47], v[46:47], v[48:49]
	s_nop 1
	v_mov_b32_dpp v49, v47 row_mirror row_mask:0xf bank_mask:0xf bound_ctrl:1
	v_mov_b32_dpp v48, v46 row_mirror row_mask:0xf bank_mask:0xf bound_ctrl:1
	v_pk_add_f32 v[46:47], v[46:47], v[48:49]
	ds_bpermute_b32 v49, v27, v47
	ds_bpermute_b32 v48, v27, v46
	s_waitcnt lgkmcnt(0)
	v_pk_add_f32 v[46:47], v[46:47], v[48:49]
	ds_bpermute_b32 v49, v28, v47
	ds_bpermute_b32 v48, v28, v46
	s_waitcnt lgkmcnt(0)
	v_pk_add_f32 v[46:47], v[46:47], v[48:49]
	s_nop 0
	v_pk_fma_f32 v[46:47], v[46:47], s[6:7], v[26:27] op_sel_hi:[1,0,0]
	s_nop 0
	v_mul_f32_e32 v29, 0x4b800000, v47
	v_cmp_gt_f32_e32 vcc, s14, v47
	v_mul_f32_e32 v48, 0x4b800000, v46
	v_cmp_gt_f32_e64 s[4:5], s14, v46
	v_cndmask_b32_e32 v29, v47, v29, vcc
	v_rsq_f32_e32 v29, v29
	v_cndmask_b32_e64 v46, v46, v48, s[4:5]
	v_rsq_f32_e32 v48, v46
	v_lshl_add_u64 v[46:47], v[24:25], 0, s[10:11]
	v_mul_f32_e32 v49, 0x45800000, v29
	v_cndmask_b32_e32 v29, v29, v49, vcc
	v_mul_f32_e32 v50, 0x45800000, v48
	v_cndmask_b32_e64 v48, v48, v50, s[4:5]
	v_mul_f32_e32 v30, v30, v29
	v_mul_f32_e32 v31, v31, v29
	v_mul_f32_e32 v32, v32, v29
	v_mul_f32_e32 v33, v33, v29
	v_mul_f32_e32 v38, v38, v48
	v_mul_f32_e32 v39, v39, v48
	v_mul_f32_e32 v30, v0, v30
	v_mul_f32_e32 v31, v1, v31
	v_mul_f32_e32 v40, v40, v48
	v_mul_f32_e32 v41, v41, v48
	v_mul_f32_e32 v32, v2, v32
	v_mul_f32_e32 v33, v3, v33
	v_mul_f32_e32 v38, v0, v38
	v_mul_f32_e32 v39, v1, v39
	v_cvt_pk_bf16_f32 v30, v30, v31
	v_cvt_pk_bf16_f32 v31, v32, v33
	v_mul_f32_e32 v40, v2, v40
	v_mul_f32_e32 v41, v3, v41
	global_store_dwordx2 v[46:47], v[30:31], off
	v_cvt_pk_bf16_f32 v38, v38, v39
	v_cvt_pk_bf16_f32 v39, v40, v41
	s_lshl_b64 s[4:5], s[8:9], 11
	v_lshl_add_u64 v[40:41], v[24:25], 0, s[4:5]
	v_mul_f32_e32 v34, v34, v29
	v_mul_f32_e32 v35, v35, v29
	v_mul_f32_e32 v36, v36, v29
	v_mul_f32_e32 v37, v37, v29
	v_mul_f32_e32 v42, v42, v48
	v_mul_f32_e32 v43, v43, v48
	v_mul_f32_e32 v44, v44, v48
	v_mul_f32_e32 v45, v45, v48
	global_store_dwordx2 v[40:41], v[38:39], off
	v_mul_f32_e32 v16, v16, v29
	v_mul_f32_e32 v17, v17, v29
	v_mul_f32_e32 v18, v18, v29
	v_mul_f32_e32 v19, v19, v29
	v_mul_f32_e32 v12, v12, v48
	v_mul_f32_e32 v13, v13, v48
	v_mul_f32_e32 v14, v14, v48
	v_mul_f32_e32 v15, v15, v48
	v_mul_f32_e32 v4, v4, v29
	v_mul_f32_e32 v5, v5, v29
	s_add_i32 s10, s8, s7
	v_mul_f32_e32 v6, v6, v29
	v_mul_f32_e32 v7, v7, v29
	v_mul_f32_e32 v8, v8, v48
	v_mul_f32_e32 v9, v9, v48
	v_mul_f32_e32 v10, v10, v48
	v_mul_f32_e32 v11, v11, v48
	s_cmpk_lt_i32 s10, 0x4000
	v_mul_f32_e32 v34, v34, v200
	v_mul_f32_e32 v35, v35, v201
	v_mul_f32_e32 v36, v36, v202
	v_mul_f32_e32 v37, v37, v203
	v_mul_f32_e32 v38, v200, v42
	v_mul_f32_e32 v39, v201, v43
	v_mul_f32_e32 v32, v202, v44
	v_mul_f32_e32 v33, v203, v45
	v_cvt_pk_bf16_f32 v30, v34, v35
	v_cvt_pk_bf16_f32 v31, v36, v37
	global_store_dwordx2 v[46:47], v[30:31], off offset:512
	v_cvt_pk_bf16_f32 v34, v38, v39
	v_cvt_pk_bf16_f32 v35, v32, v33
	v_mul_f32_e32 v16, v16, v204
	global_store_dwordx2 v[40:41], v[34:35], off offset:512
	v_mul_f32_e32 v17, v17, v205
	v_mul_f32_e32 v18, v18, v206
	v_mul_f32_e32 v19, v19, v207
	v_mul_f32_e32 v30, v12, v204
	v_mul_f32_e32 v31, v13, v205
	v_mul_f32_e32 v14, v14, v206
	v_mul_f32_e32 v15, v15, v207
	v_cvt_pk_bf16_f32 v12, v16, v17
	v_cvt_pk_bf16_f32 v13, v18, v19
	global_store_dwordx2 v[46:47], v[12:13], off offset:1024
	v_cvt_pk_bf16_f32 v16, v30, v31
	v_cvt_pk_bf16_f32 v17, v14, v15
	v_mul_f32_e32 v4, v4, v208
	v_mul_f32_e32 v5, v5, v209
	global_store_dwordx2 v[40:41], v[16:17], off offset:1024
	v_mul_f32_e32 v6, v6, v210
	v_mul_f32_e32 v7, v7, v211
	v_cvt_pk_bf16_f32 v4, v4, v5
	v_cvt_pk_bf16_f32 v5, v6, v7
	v_mul_f32_e32 v8, v8, v208
	v_mul_f32_e32 v9, v9, v209
	v_mul_f32_e32 v10, v10, v210
	v_mul_f32_e32 v11, v11, v211
	global_store_dwordx2 v[46:47], v[4:5], off offset:1536
	v_cvt_pk_bf16_f32 v4, v8, v9
	v_cvt_pk_bf16_f32 v5, v10, v11
	global_store_dwordx2 v[40:41], v[4:5], off offset:1536
	s_cbranch_scc1 .LBB0_1611
